# sample-unit K fragments: f32->bf16 by v_cvt_pk_bf16_f32 instead of the 6-instruction RNE bit trick
# speedup vs baseline: 1.0019x; 1.0019x over previous
.LBB0_1465:
	s_lshl_b32 s16, s87, 2
	s_add_u32 s14, s14, s16
	v_cmp_gt_u32_e32 vcc, s46, v174
	s_addc_u32 s15, s15, 0
	v_lshl_add_u64 v[18:19], v[162:163], 2, s[14:15]
	v_cndmask_b32_e32 v0, 0, v165, vcc
	v_lshlrev_b32_e32 v16, 2, v0
	v_lshl_add_u64 v[10:11], v[18:19], 0, v[16:17]
	v_cmp_gt_i32_e64 s[16:17], s46, v190
	v_cmp_gt_i32_e64 s[20:21], s46, v192
	v_cmp_gt_i32_e64 s[24:25], s46, v194
	v_cmp_gt_i32_e64 s[28:29], s46, v196
	v_cmp_gt_i32_e64 s[34:35], s46, v198
	v_cmp_gt_i32_e64 s[38:39], s46, v200
	v_cmp_gt_i32_e64 s[42:43], s46, v202
	v_cndmask_b32_e64 v76, 0, v192, s[20:21]
	v_cndmask_b32_e64 v84, 0, v194, s[24:25]
	v_cndmask_b32_e64 v92, 0, v196, s[28:29]
	v_cndmask_b32_e64 v100, 0, v198, s[34:35]
	v_cndmask_b32_e64 v108, 0, v200, s[38:39]
	v_cndmask_b32_e64 v116, 0, v202, s[42:43]
	v_ashrrev_i32_e32 v77, 31, v76
	v_ashrrev_i32_e32 v85, 31, v84
	v_ashrrev_i32_e32 v93, 31, v92
	v_ashrrev_i32_e32 v101, 31, v100
	v_ashrrev_i32_e32 v109, 31, v108
	v_ashrrev_i32_e32 v117, 31, v116
	v_lshlrev_b64 v[76:77], 10, v[76:77]
	v_lshlrev_b64 v[84:85], 10, v[84:85]
	v_lshlrev_b64 v[92:93], 10, v[92:93]
	v_lshlrev_b64 v[100:101], 10, v[100:101]
	v_lshlrev_b64 v[108:109], 10, v[108:109]
	v_lshlrev_b64 v[116:117], 10, v[116:117]
	v_cmp_gt_i32_e64 s[18:19], s46, v191
	v_cmp_gt_i32_e64 s[22:23], s46, v193
	v_cmp_gt_i32_e64 s[26:27], s46, v195
	v_cmp_gt_i32_e64 s[30:31], s46, v197
	v_cmp_gt_i32_e64 s[36:37], s46, v199
	v_cmp_gt_i32_e64 s[40:41], s46, v201
	v_cmp_gt_i32_e64 s[44:45], s46, v203
	v_mov_b64_e32 v[120:121], v[10:11]
	v_cmp_gt_u32_e64 s[100:101], s46, v184
	v_mov_b32_e32 v123, 0
	v_mov_b32_e32 v125, 0
	v_mov_b32_e32 v127, 0
	v_cndmask_b32_e64 v122, 0, v185, s[100:101]
	v_cmp_gt_u32_e64 s[100:101], s46, v186
	v_lshlrev_b32_e32 v122, 2, v122
	v_lshl_add_u64 v[122:123], v[18:19], 0, v[122:123]
	v_cndmask_b32_e64 v124, 0, v187, s[100:101]
	v_cmp_gt_u32_e64 s[100:101], s46, v188
	v_lshlrev_b32_e32 v124, 2, v124
	v_lshl_add_u64 v[124:125], v[18:19], 0, v[124:125]
	v_cndmask_b32_e64 v126, 0, v189, s[100:101]
	v_lshlrev_b32_e32 v126, 2, v126
	v_lshl_add_u64 v[126:127], v[18:19], 0, v[126:127]
	global_load_dwordx4 v[0:3], v[120:121], off nt
	global_load_dwordx4 v[64:67], v[120:121], off offset:16 nt
	global_load_dwordx4 v[4:7], v[120:121], off offset:128 nt
	global_load_dwordx4 v[68:71], v[120:121], off offset:144 nt
	global_load_dwordx4 v[8:11], v[122:123], off nt
	global_load_dwordx4 v[72:75], v[122:123], off offset:16 nt
	global_load_dwordx4 v[12:15], v[122:123], off offset:128 nt
	global_load_dwordx4 v[80:83], v[122:123], off offset:144 nt
	global_load_dwordx4 v[60:63], v[124:125], off nt
	global_load_dwordx4 v[88:91], v[124:125], off offset:16 nt
	global_load_dwordx4 v[128:131], v[124:125], off offset:128 nt
	global_load_dwordx4 v[96:99], v[124:125], off offset:144 nt
	global_load_dwordx4 v[132:135], v[126:127], off nt
	global_load_dwordx4 v[104:107], v[126:127], off offset:16 nt
	global_load_dwordx4 v[136:139], v[126:127], off offset:128 nt
	global_load_dwordx4 v[112:115], v[126:127], off offset:144 nt
	s_waitcnt vmcnt(14)
	v_cvt_pk_bf16_f32 v0, v0, v1
	v_cvt_pk_bf16_f32 v1, v2, v3
	v_cvt_pk_bf16_f32 v2, v64, v65
	v_cvt_pk_bf16_f32 v3, v66, v67
	s_waitcnt vmcnt(12)
	v_cvt_pk_bf16_f32 v4, v4, v5
	v_cvt_pk_bf16_f32 v5, v6, v7
	v_cvt_pk_bf16_f32 v6, v68, v69
	v_cvt_pk_bf16_f32 v7, v70, v71
	s_waitcnt vmcnt(10)
	v_cvt_pk_bf16_f32 v8, v8, v9
	v_cvt_pk_bf16_f32 v9, v10, v11
	v_cvt_pk_bf16_f32 v10, v72, v73
	v_cvt_pk_bf16_f32 v11, v74, v75
	s_waitcnt vmcnt(8)
	v_cvt_pk_bf16_f32 v12, v12, v13
	v_cvt_pk_bf16_f32 v13, v14, v15
	v_cvt_pk_bf16_f32 v14, v80, v81
	v_cvt_pk_bf16_f32 v15, v82, v83
	s_waitcnt vmcnt(6)
	v_cvt_pk_bf16_f32 v60, v60, v61
	v_cvt_pk_bf16_f32 v61, v62, v63
	v_cvt_pk_bf16_f32 v62, v88, v89
	v_cvt_pk_bf16_f32 v63, v90, v91
	s_waitcnt vmcnt(4)
	v_cvt_pk_bf16_f32 v128, v128, v129
	v_cvt_pk_bf16_f32 v129, v130, v131
	v_cvt_pk_bf16_f32 v130, v96, v97
	v_cvt_pk_bf16_f32 v131, v98, v99
	s_waitcnt vmcnt(2)
	v_cvt_pk_bf16_f32 v132, v132, v133
	v_cvt_pk_bf16_f32 v133, v134, v135
	v_cvt_pk_bf16_f32 v134, v104, v105
	v_cvt_pk_bf16_f32 v135, v106, v107
	s_waitcnt vmcnt(0)
	v_cvt_pk_bf16_f32 v136, v136, v137
	v_cvt_pk_bf16_f32 v137, v138, v139
	v_cvt_pk_bf16_f32 v138, v112, v113
	v_cvt_pk_bf16_f32 v139, v114, v115
	s_nop 1
	v_mfma_f32_16x16x32_bf16 v[0:3], v[0:3], v[36:39], 0
	v_cndmask_b32_e64 v68, 0, v190, s[16:17]
	v_lshlrev_b32_e32 v16, 2, v166
	v_ashrrev_i32_e32 v69, 31, v68
	v_lshl_add_u64 v[18:19], s[14:15], 0, v[16:17]
	v_lshlrev_b64 v[68:69], 10, v[68:69]
	v_cmp_gt_i32_e64 s[14:15], s46, v172
	v_lshl_add_u64 v[68:69], v[18:19], 0, v[68:69]
	v_lshl_add_u64 v[76:77], v[18:19], 0, v[76:77]
	v_lshl_add_u64 v[84:85], v[18:19], 0, v[84:85]
	v_lshl_add_u64 v[92:93], v[18:19], 0, v[92:93]
	v_lshl_add_u64 v[100:101], v[18:19], 0, v[100:101]
	v_lshl_add_u64 v[108:109], v[18:19], 0, v[108:109]
	v_lshl_add_u64 v[116:117], v[18:19], 0, v[116:117]
	v_cmp_gt_i32_e64 s[46:47], s46, v204
	v_cndmask_b32_e64 v64, 0, v172, s[14:15]
	global_load_dwordx4 v[72:75], v[68:69], off offset:512 nt
	global_load_dwordx4 v[80:83], v[76:77], off offset:512 nt
	v_cndmask_b32_e64 v68, 0, v191, s[18:19]
	v_cndmask_b32_e64 v76, 0, v193, s[22:23]
	global_load_dwordx4 v[88:91], v[84:85], off offset:512 nt
	global_load_dwordx4 v[96:99], v[92:93], off offset:512 nt
	v_cndmask_b32_e64 v84, 0, v195, s[26:27]
	v_cndmask_b32_e64 v92, 0, v197, s[30:31]
	global_load_dwordx4 v[104:107], v[100:101], off offset:512 nt
	global_load_dwordx4 v[112:115], v[108:109], off offset:512 nt
	v_cndmask_b32_e64 v100, 0, v199, s[36:37]
	v_cndmask_b32_e64 v108, 0, v201, s[40:41]
	global_load_dwordx4 v[120:123], v[116:117], off offset:512 nt
	v_cndmask_b32_e64 v116, 0, v203, s[44:45]
	v_cndmask_b32_e64 v124, 0, v204, s[46:47]
	v_ashrrev_i32_e32 v65, 31, v64
	v_ashrrev_i32_e32 v69, 31, v68
	v_ashrrev_i32_e32 v77, 31, v76
	v_ashrrev_i32_e32 v85, 31, v84
	v_ashrrev_i32_e32 v93, 31, v92
	v_ashrrev_i32_e32 v101, 31, v100
	v_ashrrev_i32_e32 v109, 31, v108
	v_ashrrev_i32_e32 v117, 31, v116
	v_ashrrev_i32_e32 v125, 31, v124
	v_lshlrev_b64 v[64:65], 10, v[64:65]
	v_lshlrev_b64 v[68:69], 10, v[68:69]
	v_lshlrev_b64 v[76:77], 10, v[76:77]
	v_lshlrev_b64 v[84:85], 10, v[84:85]
	v_lshlrev_b64 v[92:93], 10, v[92:93]
	v_lshlrev_b64 v[100:101], 10, v[100:101]
	v_lshlrev_b64 v[108:109], 10, v[108:109]
	v_lshlrev_b64 v[116:117], 10, v[116:117]
	v_lshlrev_b64 v[124:125], 10, v[124:125]
	v_lshl_add_u64 v[64:65], v[18:19], 0, v[64:65]
	v_lshl_add_u64 v[68:69], v[18:19], 0, v[68:69]
	v_lshl_add_u64 v[76:77], v[18:19], 0, v[76:77]
	v_lshl_add_u64 v[84:85], v[18:19], 0, v[84:85]
	v_lshl_add_u64 v[92:93], v[18:19], 0, v[92:93]
	v_lshl_add_u64 v[100:101], v[18:19], 0, v[100:101]
	v_lshl_add_u64 v[108:109], v[18:19], 0, v[108:109]
	v_lshl_add_u64 v[116:117], v[18:19], 0, v[116:117]
	v_lshl_add_u64 v[18:19], v[18:19], 0, v[124:125]
	global_load_dwordx4 v[64:67], v[64:65], off offset:512 nt
	v_lshrrev_b32_e32 v16, s48, v140
	global_load_dwordx4 v[68:71], v[68:69], off offset:512 nt
	v_mfma_f32_16x16x32_bf16 v[140:143], v[4:7], v[40:43], v[0:3]
	global_load_dwordx4 v[76:79], v[76:77], off offset:512 nt
	v_and_b32_e32 v16, 1, v16
	global_load_dwordx4 v[84:87], v[84:85], off offset:512 nt
	v_mfma_f32_16x16x32_bf16 v[0:3], v[8:11], v[36:39], 0
	global_load_dwordx4 v[92:95], v[92:93], off offset:512 nt
	v_cmp_eq_u32_e32 vcc, 1, v16
	global_load_dwordx4 v[100:103], v[100:101], off offset:512 nt
	v_mfma_f32_16x16x32_bf16 v[144:147], v[12:15], v[40:43], v[0:3]
	global_load_dwordx4 v[108:111], v[108:109], off offset:512 nt
	v_cndmask_b32_e32 v16, -1, v151, vcc
	global_load_dwordx4 v[116:119], v[116:117], off offset:512 nt
	v_mfma_f32_16x16x32_bf16 v[0:3], v[60:63], v[36:39], 0
	global_load_dwordx4 v[124:127], v[18:19], off offset:512 nt
	v_cmp_gt_u32_e32 vcc, 63, v16
	v_mfma_f32_16x16x32_bf16 v[60:63], v[128:131], v[40:43], v[0:3]
	v_mfma_f32_16x16x32_bf16 v[0:3], v[132:135], v[36:39], 0
	v_mfma_f32_16x16x32_bf16 v[128:131], v[136:139], v[40:43], v[0:3]
	s_cbranch_vccz .LBB0_1467
	v_cmp_gt_i32_e32 vcc, v160, v16
	s_or_b64 vcc, s[6:7], vcc
	s_nop 3
	v_cndmask_b32_e32 v0, v140, v246, vcc
	v_cmp_ge_i32_e32 vcc, v160, v16
	s_or_b64 vcc, s[6:7], vcc
	s_nop 0
	v_cndmask_b32_e32 v1, v141, v246, vcc
	v_cmp_gt_i32_e32 vcc, v177, v16
	s_or_b64 vcc, s[6:7], vcc
	v_max3_f32 v4, v0, s96, v1
	v_cndmask_b32_e32 v2, v142, v246, vcc
	v_cmp_gt_i32_e32 vcc, v182, v16
	s_or_b64 vcc, s[6:7], vcc
	s_nop 0
	v_cndmask_b32_e32 v3, v143, v246, vcc
	v_cmp_gt_i32_e32 vcc, v205, v16
	s_or_b64 vcc, s[8:9], vcc
	v_max3_f32 v6, v4, v2, v3
	v_cndmask_b32_e32 v4, v144, v246, vcc
	v_cmp_gt_i32_e32 vcc, v206, v16
	s_or_b64 vcc, s[8:9], vcc
	s_nop 0
	v_cndmask_b32_e32 v5, v145, v246, vcc
	v_cmp_gt_i32_e32 vcc, v207, v16
	s_or_b64 vcc, s[8:9], vcc
	v_max3_f32 v8, v6, v4, v5
	v_cndmask_b32_e32 v6, v146, v246, vcc
	v_cmp_gt_i32_e32 vcc, v208, v16
	s_or_b64 vcc, s[8:9], vcc
	s_nop 0
	v_cndmask_b32_e32 v7, v147, v246, vcc
	v_cmp_gt_i32_e32 vcc, v209, v16
	s_or_b64 vcc, s[10:11], vcc
	v_max3_f32 v10, v8, v6, v7
	v_cndmask_b32_e32 v8, v60, v246, vcc
	v_cmp_gt_i32_e32 vcc, v210, v16
	s_or_b64 vcc, s[10:11], vcc
	s_nop 0
	v_cndmask_b32_e32 v9, v61, v246, vcc
	v_cmp_gt_i32_e32 vcc, v211, v16
	s_or_b64 vcc, s[10:11], vcc
	v_max3_f32 v12, v10, v8, v9
	v_cndmask_b32_e32 v10, v62, v246, vcc
	v_cmp_gt_i32_e32 vcc, v212, v16
	s_or_b64 vcc, s[10:11], vcc
	s_nop 0
	v_cndmask_b32_e32 v11, v63, v246, vcc
	v_cmp_gt_i32_e32 vcc, v213, v16
	s_or_b64 vcc, s[12:13], vcc
	v_max3_f32 v14, v12, v10, v11
	v_cndmask_b32_e32 v12, v128, v246, vcc
	v_cmp_gt_i32_e32 vcc, v214, v16
	s_or_b64 vcc, s[12:13], vcc
	s_nop 0
	v_cndmask_b32_e32 v13, v129, v246, vcc
	v_cmp_gt_i32_e32 vcc, v215, v16
	s_or_b64 vcc, s[12:13], vcc
	v_max3_f32 v18, v14, v12, v13
	v_cndmask_b32_e32 v14, v130, v246, vcc
	v_cmp_gt_i32_e32 vcc, v216, v16
	s_or_b64 vcc, s[12:13], vcc
	s_nop 0
	v_cndmask_b32_e32 v15, v131, v246, vcc
	v_max3_f32 v18, v18, v14, v15
	s_cbranch_execnz .LBB0_1458
	s_branch .LBB0_1457

.LBB0_1472:
	s_and_b32 s6, s51, 7
	s_cmp_lg_u32 s6, s33
	s_cbranch_scc1 .LBB0_1471
	s_cmpk_eq_i32 s46, 0xfe00
	s_cselect_b32 s38, 4, 64
	v_cmp_gt_u32_e32 vcc, s38, v174
	s_cselect_b32 s7, s45, s43
	s_cselect_b32 s6, s44, s42
	v_cndmask_b32_e32 v16, 0, v165, vcc
	v_lshl_add_u64 v[18:19], v[162:163], 2, s[6:7]
	v_lshlrev_b32_e32 v16, 2, v16
	v_lshl_add_u64 v[70:71], v[18:19], 0, v[16:17]
	v_cmp_gt_i32_e64 s[8:9], s38, v190
	v_cmp_gt_i32_e64 s[12:13], s38, v192
	v_cmp_gt_i32_e64 s[16:17], s38, v194
	v_cmp_gt_i32_e64 s[20:21], s38, v196
	v_cmp_gt_i32_e64 s[24:25], s38, v198
	v_cmp_gt_i32_e64 s[28:29], s38, v200
	v_cmp_gt_i32_e64 s[34:35], s38, v202
	v_cndmask_b32_e64 v92, 0, v192, s[12:13]
	v_cndmask_b32_e64 v100, 0, v194, s[16:17]
	v_cndmask_b32_e64 v108, 0, v196, s[20:21]
	v_cndmask_b32_e64 v116, 0, v198, s[24:25]
	v_cndmask_b32_e64 v124, 0, v200, s[28:29]
	v_cndmask_b32_e64 v132, 0, v202, s[34:35]
	v_ashrrev_i32_e32 v93, 31, v92
	v_ashrrev_i32_e32 v101, 31, v100
	v_ashrrev_i32_e32 v109, 31, v108
	v_ashrrev_i32_e32 v117, 31, v116
	v_ashrrev_i32_e32 v125, 31, v124
	v_ashrrev_i32_e32 v133, 31, v132
	v_lshlrev_b64 v[92:93], 10, v[92:93]
	v_lshlrev_b64 v[100:101], 10, v[100:101]
	v_lshlrev_b64 v[108:109], 10, v[108:109]
	v_lshlrev_b64 v[116:117], 10, v[116:117]
	v_lshlrev_b64 v[124:125], 10, v[124:125]
	v_lshlrev_b64 v[132:133], 10, v[132:133]
	v_cmp_gt_i32_e64 s[10:11], s38, v191
	v_cmp_gt_i32_e64 s[14:15], s38, v193
	v_cmp_gt_i32_e64 s[18:19], s38, v195
	v_cmp_gt_i32_e64 s[22:23], s38, v197
	v_cmp_gt_i32_e64 s[26:27], s38, v199
	v_cmp_gt_i32_e64 s[30:31], s38, v201
	v_cmp_gt_i32_e64 s[36:37], s38, v203
	v_mov_b64_e32 v[140:141], v[70:71]
	v_cmp_gt_u32_e64 s[100:101], s38, v184
	v_mov_b32_e32 v143, 0
	v_mov_b32_e32 v251, 0
	v_mov_b32_e32 v253, 0
	v_cndmask_b32_e64 v142, 0, v185, s[100:101]
	v_cmp_gt_u32_e64 s[100:101], s38, v186
	v_lshlrev_b32_e32 v142, 2, v142
	v_lshl_add_u64 v[142:143], v[18:19], 0, v[142:143]
	v_cndmask_b32_e64 v250, 0, v187, s[100:101]
	v_cmp_gt_u32_e64 s[100:101], s38, v188
	v_lshlrev_b32_e32 v250, 2, v250
	v_lshl_add_u64 v[250:251], v[18:19], 0, v[250:251]
	v_cndmask_b32_e64 v252, 0, v189, s[100:101]
	v_lshlrev_b32_e32 v252, 2, v252
	v_lshl_add_u64 v[252:253], v[18:19], 0, v[252:253]
	global_load_dwordx4 v[60:63], v[140:141], off nt
	global_load_dwordx4 v[80:83], v[140:141], off offset:16 nt
	global_load_dwordx4 v[64:67], v[140:141], off offset:128 nt
	global_load_dwordx4 v[88:91], v[140:141], off offset:144 nt
	global_load_dwordx4 v[68:71], v[142:143], off nt
	global_load_dwordx4 v[96:99], v[142:143], off offset:16 nt
	global_load_dwordx4 v[72:75], v[142:143], off offset:128 nt
	global_load_dwordx4 v[104:107], v[142:143], off offset:144 nt
	global_load_dwordx4 v[76:79], v[250:251], off nt
	global_load_dwordx4 v[112:115], v[250:251], off offset:16 nt
	global_load_dwordx4 v[144:147], v[250:251], off offset:128 nt
	global_load_dwordx4 v[120:123], v[250:251], off offset:144 nt
	global_load_dwordx4 v[148:151], v[252:253], off nt
	global_load_dwordx4 v[128:131], v[252:253], off offset:16 nt
	global_load_dwordx4 v[152:155], v[252:253], off offset:128 nt
	global_load_dwordx4 v[136:139], v[252:253], off offset:144 nt
	s_waitcnt vmcnt(14)
	v_cvt_pk_bf16_f32 v60, v60, v61
	v_cvt_pk_bf16_f32 v61, v62, v63
	v_cvt_pk_bf16_f32 v62, v80, v81
	v_cvt_pk_bf16_f32 v63, v82, v83
	s_waitcnt vmcnt(12)
	v_cvt_pk_bf16_f32 v64, v64, v65
	v_cvt_pk_bf16_f32 v65, v66, v67
	v_cvt_pk_bf16_f32 v66, v88, v89
	v_cvt_pk_bf16_f32 v67, v90, v91
	s_waitcnt vmcnt(10)
	v_cvt_pk_bf16_f32 v68, v68, v69
	v_cvt_pk_bf16_f32 v69, v70, v71
	v_cvt_pk_bf16_f32 v70, v96, v97
	v_cvt_pk_bf16_f32 v71, v98, v99
	s_waitcnt vmcnt(8)
	v_cvt_pk_bf16_f32 v72, v72, v73
	v_cvt_pk_bf16_f32 v73, v74, v75
	v_cvt_pk_bf16_f32 v74, v104, v105
	v_cvt_pk_bf16_f32 v75, v106, v107
	s_waitcnt vmcnt(6)
	v_cvt_pk_bf16_f32 v76, v76, v77
	v_cvt_pk_bf16_f32 v77, v78, v79
	v_cvt_pk_bf16_f32 v78, v112, v113
	v_cvt_pk_bf16_f32 v79, v114, v115
	s_waitcnt vmcnt(4)
	v_cvt_pk_bf16_f32 v144, v144, v145
	v_cvt_pk_bf16_f32 v145, v146, v147
	v_cvt_pk_bf16_f32 v146, v120, v121
	v_cvt_pk_bf16_f32 v147, v122, v123
	s_waitcnt vmcnt(2)
	v_cvt_pk_bf16_f32 v148, v148, v149
	v_cvt_pk_bf16_f32 v149, v150, v151
	v_cvt_pk_bf16_f32 v150, v128, v129
	v_cvt_pk_bf16_f32 v151, v130, v131
	s_waitcnt vmcnt(0)
	v_cvt_pk_bf16_f32 v152, v152, v153
	v_cvt_pk_bf16_f32 v153, v154, v155
	v_cvt_pk_bf16_f32 v154, v136, v137
	v_cvt_pk_bf16_f32 v155, v138, v139
	s_nop 1
	v_mfma_f32_16x16x32_bf16 v[60:63], v[60:63], v[36:39], 0
	v_mfma_f32_16x16x32_bf16 v[60:63], v[64:67], v[40:43], v[60:63]
	v_mfma_f32_16x16x32_bf16 v[64:67], v[68:71], v[36:39], 0
	v_mfma_f32_16x16x32_bf16 v[64:67], v[72:75], v[40:43], v[64:67]
	v_mfma_f32_16x16x32_bf16 v[68:71], v[76:79], v[36:39], 0
	v_mfma_f32_16x16x32_bf16 v[72:75], v[148:151], v[36:39], 0
	v_cndmask_b32_e64 v84, 0, v190, s[8:9]
	v_lshlrev_b32_e32 v16, 2, v166
	v_ashrrev_i32_e32 v85, 31, v84
	v_lshl_add_u64 v[18:19], s[6:7], 0, v[16:17]
	v_lshlrev_b64 v[84:85], 10, v[84:85]
	v_cmp_gt_i32_e64 s[6:7], s38, v172
	v_lshl_add_u64 v[84:85], v[18:19], 0, v[84:85]
	v_lshl_add_u64 v[92:93], v[18:19], 0, v[92:93]
	v_lshl_add_u64 v[100:101], v[18:19], 0, v[100:101]
	v_lshl_add_u64 v[108:109], v[18:19], 0, v[108:109]
	v_lshl_add_u64 v[116:117], v[18:19], 0, v[116:117]
	v_lshl_add_u64 v[124:125], v[18:19], 0, v[124:125]
	v_lshl_add_u64 v[132:133], v[18:19], 0, v[132:133]
	v_cmp_gt_i32_e64 s[38:39], s38, v204
	v_cndmask_b32_e64 v80, 0, v172, s[6:7]
	global_load_dwordx4 v[88:91], v[84:85], off offset:512 nt
	global_load_dwordx4 v[96:99], v[92:93], off offset:512 nt
	v_cndmask_b32_e64 v84, 0, v191, s[10:11]
	v_cndmask_b32_e64 v92, 0, v193, s[14:15]
	global_load_dwordx4 v[104:107], v[100:101], off offset:512 nt
	global_load_dwordx4 v[112:115], v[108:109], off offset:512 nt
	v_cndmask_b32_e64 v100, 0, v195, s[18:19]
	v_cndmask_b32_e64 v108, 0, v197, s[22:23]
	global_load_dwordx4 v[120:123], v[116:117], off offset:512 nt
	global_load_dwordx4 v[128:131], v[124:125], off offset:512 nt
	v_cndmask_b32_e64 v116, 0, v199, s[26:27]
	v_cndmask_b32_e64 v124, 0, v201, s[30:31]
	global_load_dwordx4 v[136:139], v[132:133], off offset:512 nt
	v_cndmask_b32_e64 v132, 0, v203, s[36:37]
	v_cndmask_b32_e64 v140, 0, v204, s[38:39]
	v_ashrrev_i32_e32 v81, 31, v80
	v_ashrrev_i32_e32 v85, 31, v84
	v_ashrrev_i32_e32 v93, 31, v92
	v_ashrrev_i32_e32 v101, 31, v100
	v_ashrrev_i32_e32 v109, 31, v108
	v_ashrrev_i32_e32 v117, 31, v116
	v_ashrrev_i32_e32 v125, 31, v124
	v_ashrrev_i32_e32 v133, 31, v132
	v_ashrrev_i32_e32 v141, 31, v140
	v_lshlrev_b64 v[80:81], 10, v[80:81]
	v_lshlrev_b64 v[84:85], 10, v[84:85]
	v_lshlrev_b64 v[92:93], 10, v[92:93]
	v_lshlrev_b64 v[100:101], 10, v[100:101]
	v_lshlrev_b64 v[108:109], 10, v[108:109]
	v_lshlrev_b64 v[116:117], 10, v[116:117]
	v_lshlrev_b64 v[124:125], 10, v[124:125]
	v_lshlrev_b64 v[132:133], 10, v[132:133]
	v_lshlrev_b64 v[140:141], 10, v[140:141]
	v_lshl_add_u64 v[80:81], v[18:19], 0, v[80:81]
	v_lshl_add_u64 v[84:85], v[18:19], 0, v[84:85]
	v_lshl_add_u64 v[92:93], v[18:19], 0, v[92:93]
	v_lshl_add_u64 v[100:101], v[18:19], 0, v[100:101]
	v_lshl_add_u64 v[108:109], v[18:19], 0, v[108:109]
	v_lshl_add_u64 v[116:117], v[18:19], 0, v[116:117]
	v_lshl_add_u64 v[124:125], v[18:19], 0, v[124:125]
	v_lshl_add_u64 v[132:133], v[18:19], 0, v[132:133]
	v_lshl_add_u64 v[18:19], v[18:19], 0, v[140:141]
	global_load_dwordx4 v[80:83], v[80:81], off offset:512 nt
	v_mfma_f32_16x16x32_bf16 v[68:71], v[144:147], v[40:43], v[68:71]
	global_load_dwordx4 v[84:87], v[84:85], off offset:512 nt
	s_nop 0
	global_load_dwordx4 v[92:95], v[92:93], off offset:512 nt
	v_mfma_f32_16x16x32_bf16 v[72:75], v[152:155], v[40:43], v[72:75]
	global_load_dwordx4 v[100:103], v[100:101], off offset:512 nt
	s_nop 0
	global_load_dwordx4 v[108:111], v[108:109], off offset:512 nt
	s_nop 0
	global_load_dwordx4 v[116:119], v[116:117], off offset:512 nt
	s_nop 0
	global_load_dwordx4 v[124:127], v[124:125], off offset:512 nt
	s_nop 0
	global_load_dwordx4 v[132:135], v[132:133], off offset:512 nt
	s_nop 0
	global_load_dwordx4 v[140:143], v[18:19], off offset:512 nt
	v_add_u32_e32 v18, s46, v173
	v_add_u32_e32 v16, 1, v18
	v_add_u32_e32 v18, 0x200, v18
	v_cmp_lt_i32_e32 vcc, 0, v16
	v_cmp_gt_u32_e64 s[40:41], 63, v18
	s_or_b64 vcc, vcc, s[40:41]
	s_cbranch_vccz .LBB0_1475
	v_cmp_lt_i32_e32 vcc, v160, v16
	v_cmp_gt_i32_e64 s[40:41], v160, v18
	s_or_b64 vcc, vcc, s[40:41]
	v_cndmask_b32_e32 v154, v60, v246, vcc
	v_cmp_lt_i32_e32 vcc, v176, v16
	v_cmp_ge_i32_e64 s[40:41], v160, v18
	s_or_b64 vcc, vcc, s[40:41]
	v_cndmask_b32_e32 v153, v61, v246, vcc
	v_cmp_lt_i32_e32 vcc, v177, v16
	v_cmp_gt_i32_e64 s[40:41], v177, v18
	s_or_b64 vcc, vcc, s[40:41]
	v_cndmask_b32_e32 v152, v62, v246, vcc
	v_cmp_lt_i32_e32 vcc, v182, v16
	v_cmp_gt_i32_e64 s[40:41], v182, v18
	s_or_b64 vcc, vcc, s[40:41]
	v_cndmask_b32_e32 v151, v63, v246, vcc
	v_cmp_lt_i32_e32 vcc, v205, v16
	v_cmp_gt_i32_e64 s[40:41], v205, v18
	s_or_b64 vcc, vcc, s[40:41]
	v_cndmask_b32_e32 v150, v64, v246, vcc
	v_cmp_lt_i32_e32 vcc, v206, v16
	v_cmp_gt_i32_e64 s[40:41], v206, v18
	s_or_b64 vcc, vcc, s[40:41]
	v_cndmask_b32_e32 v149, v65, v246, vcc
	v_cmp_lt_i32_e32 vcc, v207, v16
	v_cmp_gt_i32_e64 s[40:41], v207, v18
	s_or_b64 vcc, vcc, s[40:41]
	v_cndmask_b32_e32 v148, v66, v246, vcc
	v_cmp_lt_i32_e32 vcc, v208, v16
	v_cmp_gt_i32_e64 s[40:41], v208, v18
	s_or_b64 vcc, vcc, s[40:41]
	v_cndmask_b32_e32 v147, v67, v246, vcc
	v_cmp_lt_i32_e32 vcc, v209, v16
	v_cmp_gt_i32_e64 s[40:41], v209, v18
	s_or_b64 vcc, vcc, s[40:41]
	v_cndmask_b32_e32 v146, v68, v246, vcc
	v_cmp_lt_i32_e32 vcc, v210, v16
	v_cmp_gt_i32_e64 s[40:41], v210, v18
	s_or_b64 vcc, vcc, s[40:41]
	v_cndmask_b32_e32 v145, v69, v246, vcc
	v_cmp_lt_i32_e32 vcc, v211, v16
	v_cmp_gt_i32_e64 s[40:41], v211, v18
	s_or_b64 vcc, vcc, s[40:41]
	v_cndmask_b32_e32 v144, v70, v246, vcc
	v_cmp_lt_i32_e32 vcc, v212, v16
	v_cmp_gt_i32_e64 s[40:41], v212, v18
	s_or_b64 vcc, vcc, s[40:41]
	v_cndmask_b32_e32 v79, v71, v246, vcc
	v_cmp_lt_i32_e32 vcc, v213, v16
	v_cmp_gt_i32_e64 s[40:41], v213, v18
	s_or_b64 vcc, vcc, s[40:41]
	v_max3_f32 v19, v154, s96, v153
	v_cndmask_b32_e32 v78, v72, v246, vcc
	v_cmp_lt_i32_e32 vcc, v214, v16
	v_cmp_gt_i32_e64 s[40:41], v214, v18
	v_max3_f32 v19, v19, v152, v151
	s_or_b64 vcc, vcc, s[40:41]
	v_max3_f32 v19, v19, v150, v149
	v_cndmask_b32_e32 v77, v73, v246, vcc
	v_cmp_lt_i32_e32 vcc, v215, v16
	v_cmp_gt_i32_e64 s[40:41], v215, v18
	v_max3_f32 v19, v19, v148, v147
	s_or_b64 vcc, vcc, s[40:41]
	v_max3_f32 v19, v19, v146, v145
	v_cndmask_b32_e32 v76, v74, v246, vcc
	v_cmp_lt_i32_e32 vcc, v216, v16
	v_cmp_gt_i32_e64 s[40:41], v216, v18
	v_max3_f32 v19, v19, v144, v79
	s_or_b64 vcc, vcc, s[40:41]
	v_max3_f32 v19, v19, v78, v77
	v_cndmask_b32_e32 v18, v75, v246, vcc
	v_max3_f32 v16, v19, v76, v18
	s_cbranch_execnz .LBB0_1470
	s_branch .LBB0_1469
